# cmp_task: V^T tile staged by LDS-DMA into the wave's private LDS at task start; PV fragments read with ds_read_b64 instead of serialized global loads
# baseline (speedup 1.0000x reference)
; #define MFMA32(a, b, c) __builtin_amdgcn_mfma_f32_32x32x16_bf16((a), (b), (c), 0, 0, 0)
; DI int crow(int r, int h) { return (r & 3) + 8 * (r >> 2) + 4 * h; }
; DI void cmp_task(const bf16_t* Z, const bf16_t* KCC, const bf16_t* VCT, bf16_t* OCMP, unsigned* selm, int b, int hk, int tg, int lane) {
;     const int r32 = lane & 31, h = lane >> 5;
;     const int tok = 8 * tg + (r32 >> 2), g = r32 & 3, head = hk * 4 + g;
;     const size_t grow = (size_t)b * SEQ + tok;
;     const bf16_t* zr = Z + grow * NZ;
;     bf16x8 qf[4];
; #pragma unroll
;     for (int s = 0; s < 4; ++s) qf[s] = *(const bf16x8*)(zr + ZC_QA + head * 64 + 16 * s + 8 * h);
;     const bf16_t* kc = KCC + (size_t)(b * 2 + hk) * 128 * 64; const bf16_t* vt = VCT + (size_t)(b * 2 + hk) * 64 * 128;
;     const int tmax = 8 * tg + 7;
;     const int nsub = tmax < 31 ? 0 : (((tmax - 31) >> 4) >> 5) + 1;
;     f32x16 p[4];
; #pragma unroll
;     for (int sub = 0; sub < 4; ++sub) {
;         if (sub < nsub) {
;             p[sub] = f16zero();
; #pragma unroll
;             for (int s = 0; s < 4; ++s) { const bf16x8 af = *(const bf16x8*)(kc + (size_t)(32 * sub + r32) * 64 + 16 * s + 8 * h); p[sub] = MFMA32(af, qf[s], p[sub]); }
; #pragma unroll
;             for (int r = 0; r < 16; ++r) { const int n = 32 * sub + crow(r, h); p[sub][r] = (16 * n + 31 <= tok) ? p[sub][r] * SM_C : NINF; }
.LBB0_481:
	s_mul_i32 s8, s63, s20
	s_add_i32 s9, s8, s92
	s_lshr_b32 s10, s9, 5
	s_and_b32 s10, s10, 0xc0
	s_add_i32 s10, s10, s9
	s_ashr_i32 s8, s9, 9
	s_and_b32 s54, s10, 0xff
	s_bfe_u32 s14, s9, 0x10008
	s_lshl_b32 s50, s54, 3
	s_ashr_i32 s9, s8, 31
	v_or_b32_e32 v131, s50, v113
	s_lshl_b64 s[10:11], s[8:9], 11
	v_or_b32_e32 v122, s10, v131
	v_mov_b64_e32 v[2:3], s[22:23]
	s_movk_i32 s9, 0x2200
	v_mad_u64_u32 v[2:3], s[48:49], v122, s9, v[2:3]
	v_lshl_or_b32 v1, s14, 8, v115
	v_mad_i32_i24 v3, s11, v244, v3
	v_lshlrev_b32_e32 v42, 1, v1
	v_lshl_add_u64 v[2:3], v[2:3], 0, v[42:43]
	v_mov_b32_e32 v41, v43
	v_lshl_add_u64 v[2:3], v[2:3], 0, v[40:41]
	global_load_dwordx4 v[30:33], v[2:3], off
	global_load_dwordx4 v[26:29], v[2:3], off offset:32
	global_load_dwordx4 v[22:25], v[2:3], off offset:64
	global_load_dwordx4 v[18:21], v[2:3], off offset:96
	s_lshl_b32 s8, s8, 1
	s_or_b32 s8, s8, s14
	s_ashr_i32 s9, s8, 31
	s_lshl_b64 s[8:9], s[8:9], 14
	s_or_b32 s10, s50, 7
	s_cmp_lt_u32 s10, 31
	s_cselect_b64 s[48:49], -1, 0
	s_cmp_gt_u32 s10, 30
	v_mov_b32_e32 v123, s11
	s_cselect_b64 s[10:11], -1, 0
	v_lshl_add_u64 v[124:125], v[44:45], 0, s[8:9]
	v_readfirstlane_b32 s99, v0
	s_lshr_b32 s99, s99, 6
	s_lshl_b32 s99, s99, 14
	v_readfirstlane_b32 s78, v78
	v_readfirstlane_b32 s79, v79
	s_add_u32 s78, s78, s8
	s_addc_u32 s79, s79, s9
	v_mbcnt_lo_u32_b32 v34, -1, 0
	v_mbcnt_hi_u32_b32 v34, -1, v34
	v_lshrrev_b32_e32 v35, 5, v34
	v_and_b32_e32 v34, 31, v34
	v_lshlrev_b32_e32 v34, 8, v34
	v_lshl_or_b32 v34, v35, 4, v34
	s_add_i32 m0, s99, 0x0
	s_add_u32 s80, s78, 0x0
	s_addc_u32 s81, s79, 0
	global_load_lds_dwordx4 v34, s[80:81]
	s_add_i32 m0, s99, 0x400
	s_add_u32 s80, s78, 0x20
	s_addc_u32 s81, s79, 0
	global_load_lds_dwordx4 v34, s[80:81]
	s_add_i32 m0, s99, 0x800
	s_add_u32 s80, s78, 0x40
	s_addc_u32 s81, s79, 0
	global_load_lds_dwordx4 v34, s[80:81]
	s_add_i32 m0, s99, 0xc00
	s_add_u32 s80, s78, 0x60
	s_addc_u32 s81, s79, 0
	global_load_lds_dwordx4 v34, s[80:81]
	s_add_i32 m0, s99, 0x1000
	s_add_u32 s80, s78, 0x80
	s_addc_u32 s81, s79, 0
	global_load_lds_dwordx4 v34, s[80:81]
	s_add_i32 m0, s99, 0x1400
	s_add_u32 s80, s78, 0xa0
	s_addc_u32 s81, s79, 0
	global_load_lds_dwordx4 v34, s[80:81]
	s_add_i32 m0, s99, 0x1800
	s_add_u32 s80, s78, 0xc0
	s_addc_u32 s81, s79, 0
	global_load_lds_dwordx4 v34, s[80:81]
	s_add_i32 m0, s99, 0x1c00
	s_add_u32 s80, s78, 0xe0
	s_addc_u32 s81, s79, 0
	global_load_lds_dwordx4 v34, s[80:81]
	s_add_i32 m0, s99, 0x2000
	s_add_u32 s80, s78, 0x2000
	s_addc_u32 s81, s79, 0
	global_load_lds_dwordx4 v34, s[80:81]
	s_add_i32 m0, s99, 0x2400
	s_add_u32 s80, s78, 0x2020
	s_addc_u32 s81, s79, 0
	global_load_lds_dwordx4 v34, s[80:81]
	s_add_i32 m0, s99, 0x2800
	s_add_u32 s80, s78, 0x2040
	s_addc_u32 s81, s79, 0
	global_load_lds_dwordx4 v34, s[80:81]
	s_add_i32 m0, s99, 0x2c00
	s_add_u32 s80, s78, 0x2060
	s_addc_u32 s81, s79, 0
	global_load_lds_dwordx4 v34, s[80:81]
	s_add_i32 m0, s99, 0x3000
	s_add_u32 s80, s78, 0x2080
	s_addc_u32 s81, s79, 0
	global_load_lds_dwordx4 v34, s[80:81]
	s_add_i32 m0, s99, 0x3400
	s_add_u32 s80, s78, 0x20a0
	s_addc_u32 s81, s79, 0
	global_load_lds_dwordx4 v34, s[80:81]
	s_add_i32 m0, s99, 0x3800
	s_add_u32 s80, s78, 0x20c0
	s_addc_u32 s81, s79, 0
	global_load_lds_dwordx4 v34, s[80:81]
	s_add_i32 m0, s99, 0x3c00
	s_add_u32 s80, s78, 0x20e0
	s_addc_u32 s81, s79, 0
	global_load_lds_dwordx4 v34, s[80:81]
	v_mov_b32_e32 v121, 0xff800000
	s_and_b64 vcc, exec, s[48:49]
	v_lshlrev_b32_e32 v126, 1, v38
	v_mov_b32_e32 v128, 0xff800000
	v_mov_b32_e32 v129, 0xff800000
	v_mov_b32_e32 v130, 0xff800000
	v_mov_b32_e32 v134, 0xff800000
	v_mov_b32_e32 v135, 0xff800000
	v_mov_b32_e32 v139, 0xff800000
	v_mov_b32_e32 v140, 0xff800000
	v_mov_b32_e32 v141, 0xff800000
	v_mov_b32_e32 v142, 0xff800000
	v_mov_b32_e32 v143, 0xff800000
	v_mov_b32_e32 v144, 0xff800000
	v_mov_b32_e32 v145, 0xff800000
	v_mov_b32_e32 v146, 0xff800000
	v_mov_b32_e32 v147, 0xff800000
	v_mov_b32_e32 v148, 0xff800000
	v_mov_b32_e32 v149, 0xff800000
	s_cbranch_vccnz .LBB0_483
	v_mov_b32_e32 v127, v43
	v_lshl_add_u64 v[94:95], v[124:125], 0, v[126:127]
	global_load_dwordx4 v[2:5], v[94:95], off
	global_load_dwordx4 v[140:143], v[94:95], off offset:32
	global_load_dwordx4 v[150:153], v[94:95], off offset:64
	global_load_dwordx4 v[154:157], v[94:95], off offset:96
	v_cmp_le_u32_e32 vcc, v46, v131
	s_waitcnt vmcnt(3)
	v_mfma_f32_32x32x16_bf16 v[2:17], v[2:5], v[30:33], 0
	s_waitcnt vmcnt(2)
	v_mfma_f32_32x32x16_bf16 v[2:17], v[140:143], v[26:29], v[2:17]
	s_waitcnt vmcnt(1)
	v_mfma_f32_32x32x16_bf16 v[2:17], v[150:153], v[22:25], v[2:17]
	s_waitcnt vmcnt(0)
	v_mfma_f32_32x32x16_bf16 v[2:17], v[154:157], v[18:21], v[2:17]
	s_nop 11
	v_pk_mul_f32 v[2:3], v[2:3], s[46:47] op_sel_hi:[1,0]
	s_nop 0
	v_cndmask_b32_e32 v128, v245, v2, vcc
	v_cmp_le_u32_e32 vcc, v37, v131
	v_mul_f32_e32 v1, 0x3e38aa3b, v4
	s_nop 0
	v_cndmask_b32_e32 v129, v245, v3, vcc
	v_cmp_le_u32_e32 vcc, v117, v131
	v_pk_mul_f32 v[2:3], v[6:7], s[46:47] op_sel_hi:[1,0]
	s_nop 0
	v_cndmask_b32_e32 v130, v245, v1, vcc
	v_mul_f32_e32 v1, 0x3e38aa3b, v5
	v_cmp_le_u32_e32 vcc, v119, v131
	s_nop 1
	v_cndmask_b32_e32 v134, v245, v1, vcc
	v_cmp_le_u32_e32 vcc, v48, v131
	v_mul_f32_e32 v1, 0x3e38aa3b, v8
	s_nop 0
	v_cndmask_b32_e32 v135, v245, v2, vcc
	v_cmp_le_u32_e32 vcc, v39, v131
	s_nop 1
	v_cndmask_b32_e32 v139, v245, v3, vcc
	v_cmp_le_u32_e32 vcc, v202, v131
	v_pk_mul_f32 v[2:3], v[10:11], s[46:47] op_sel_hi:[1,0]
	s_nop 0
	v_cndmask_b32_e32 v140, v245, v1, vcc
	v_mul_f32_e32 v1, 0x3e38aa3b, v9
	v_cmp_le_u32_e32 vcc, v203, v131
	s_nop 1
	v_cndmask_b32_e32 v141, v245, v1, vcc
	v_cmp_le_u32_e32 vcc, v50, v131
	v_mul_f32_e32 v1, 0x3e38aa3b, v12
	s_nop 0
	v_cndmask_b32_e32 v142, v245, v2, vcc
	v_cmp_le_u32_e32 vcc, v47, v131
	s_nop 1
	v_cndmask_b32_e32 v143, v245, v3, vcc
	v_cmp_le_u32_e32 vcc, v204, v131
	v_pk_mul_f32 v[2:3], v[14:15], s[46:47] op_sel_hi:[1,0]
	s_nop 0
	v_cndmask_b32_e32 v144, v245, v1, vcc
	v_mul_f32_e32 v1, 0x3e38aa3b, v13
	v_cmp_le_u32_e32 vcc, v205, v131
	s_nop 1
	v_cndmask_b32_e32 v145, v245, v1, vcc
	v_cmp_le_u32_e32 vcc, v52, v131
	v_mul_f32_e32 v1, 0x3e38aa3b, v16
	s_nop 0
	v_cndmask_b32_e32 v146, v245, v2, vcc
	v_cmp_le_u32_e32 vcc, v49, v131
	s_nop 1
	v_cndmask_b32_e32 v147, v245, v3, vcc
	v_cmp_le_u32_e32 vcc, v206, v131
	s_nop 1
	v_cndmask_b32_e32 v148, v245, v1, vcc
	v_mul_f32_e32 v1, 0x3e38aa3b, v17
	v_cmp_le_u32_e32 vcc, v207, v131
	s_nop 1
	v_cndmask_b32_e32 v149, v245, v1, vcc

; DI float fexp2(float x) { return __builtin_amdgcn_exp2f(x); }
; DI void cmp_task(const bf16_t* Z, const bf16_t* KCC, const bf16_t* VCT, bf16_t* OCMP, unsigned* selm, int b, int hk, int tg, int lane) {
;     ...
;     float mx = NINF;
; #pragma unroll
;     for (int sub = 0; sub < 4; ++sub)
; #pragma unroll
;         for (int r = 0; r < 16; ++r) mx = fmaxf(mx, p[sub][r]);
;     mx = fmaxf(mx, __shfl_xor(mx, 32));
;     const float mu = (mx == NINF) ? 0.f : mx;
;     float sum = 0.f;
; #pragma unroll
;     for (int sub = 0; sub < 4; ++sub)
; #pragma unroll
;         for (int r = 0; r < 16; ++r) { p[sub][r] = fexp2(p[sub][r] - mu); sum += p[sub][r]; }
;     const float lt = sum + __shfl_xor(sum, 32); const float inv = lt > 0.f ? 1.0f / lt : 0.f;
.LBB0_489:
	v_max3_f32 v2, v128, s61, v129
	v_max3_f32 v2, v2, v130, v134
	v_max3_f32 v2, v2, v135, v139
	v_max3_f32 v2, v2, v140, v141
	v_max3_f32 v2, v2, v142, v143
	v_max3_f32 v2, v2, v144, v145
	v_max3_f32 v2, v2, v146, v147
	v_max3_f32 v2, v2, v148, v149
	v_max3_f32 v2, v2, v121, v150
	v_max3_f32 v2, v2, v151, v152
	v_max3_f32 v2, v2, v153, v154
	v_max3_f32 v2, v2, v155, v156
	v_max3_f32 v2, v2, v157, v158
	v_max3_f32 v2, v2, v159, v160
	v_max3_f32 v2, v2, v161, v162
	v_max3_f32 v2, v2, v163, v164
	v_max3_f32 v2, v2, v166, v167
	v_max3_f32 v2, v2, v174, v175
	v_max3_f32 v2, v2, v190, v191
	v_max3_f32 v2, v2, v192, v193
	v_max3_f32 v2, v2, v194, v195
	v_max3_f32 v2, v2, v196, v197
	v_max3_f32 v2, v2, v247, v248
	v_max3_f32 v2, v2, v249, v250
	v_max3_f32 v2, v2, v165, v127
	v_max3_f32 v2, v2, v251, v252
	v_max3_f32 v2, v2, v215, v34
	v_max3_f32 v2, v2, v137, v1
	v_and_b32_e32 v4, 64, v246
	v_max3_f32 v2, v2, v234, v75
	v_xor_b32_e32 v3, 32, v246
	v_add_u32_e32 v4, 64, v4
	v_max3_f32 v2, v2, v82, v77
	v_cmp_lt_i32_e32 vcc, v3, v4
	v_max3_f32 v2, v2, v14, v15
	v_max3_f32 v2, v2, v16, v17
	v_cndmask_b32_e32 v3, v246, v3, vcc
	v_lshlrev_b32_e32 v41, 2, v3
	ds_bpermute_b32 v3, v41, v2
	s_waitcnt lgkmcnt(0)
	v_max_f32_e32 v3, v3, v3
	v_max_f32_e32 v2, v2, v3
	v_cmp_neq_f32_e32 vcc, s61, v2
	s_waitcnt vmcnt(3)
	s_nop 0
	v_cndmask_b32_e32 v30, 0, v2, vcc
	v_sub_f32_e32 v2, v128, v30
	v_exp_f32_e32 v12, v2
	v_sub_f32_e32 v2, v129, v30
	v_exp_f32_e32 v10, v2
	v_sub_f32_e32 v2, v130, v30
	v_exp_f32_e32 v13, v2
	v_sub_f32_e32 v2, v134, v30
	v_exp_f32_e32 v11, v2
	v_add_f32_e32 v2, 0, v12
	v_add_f32_e32 v2, v10, v2
	v_add_f32_e32 v2, v13, v2
	v_add_f32_e32 v3, v11, v2
	v_sub_f32_e32 v2, v135, v30
	v_exp_f32_e32 v8, v2
	v_sub_f32_e32 v2, v139, v30
	v_exp_f32_e32 v6, v2
	v_sub_f32_e32 v2, v140, v30
	v_exp_f32_e32 v4, v2
	v_sub_f32_e32 v2, v141, v30
	v_exp_f32_e32 v2, v2
	v_sub_f32_e32 v5, v142, v30
	v_add_f32_e32 v3, v8, v3
	s_waitcnt vmcnt(0)
	v_exp_f32_e32 v18, v5
	v_sub_f32_e32 v5, v143, v30
	v_add_f32_e32 v3, v6, v3
	v_exp_f32_e32 v19, v5
	v_sub_f32_e32 v5, v144, v30
	v_add_f32_e32 v3, v4, v3
	v_exp_f32_e32 v20, v5
	v_sub_f32_e32 v5, v145, v30
	v_add_f32_e32 v3, v2, v3
	v_exp_f32_e32 v21, v5
	v_add_f32_e32 v3, v18, v3
	v_add_f32_e32 v3, v19, v3
	v_add_f32_e32 v3, v20, v3
	v_add_f32_e32 v22, v21, v3
	v_sub_f32_e32 v3, v146, v30
	v_exp_f32_e32 v9, v3
	v_sub_f32_e32 v3, v147, v30
	v_exp_f32_e32 v7, v3
	v_sub_f32_e32 v3, v148, v30
	v_exp_f32_e32 v5, v3
	v_sub_f32_e32 v3, v149, v30
	v_exp_f32_e32 v3, v3
	v_sub_f32_e32 v23, v121, v30
	v_add_f32_e32 v22, v9, v22
	v_exp_f32_e32 v168, v23
	v_sub_f32_e32 v23, v150, v30
	v_add_f32_e32 v22, v7, v22
	v_exp_f32_e32 v169, v23
	v_sub_f32_e32 v23, v151, v30
	v_add_f32_e32 v22, v5, v22
	v_exp_f32_e32 v170, v23
	v_sub_f32_e32 v23, v152, v30
	v_add_f32_e32 v22, v3, v22
	v_exp_f32_e32 v171, v23
	v_sub_f32_e32 v23, v153, v30
	v_add_f32_e32 v22, v168, v22
	v_exp_f32_e32 v172, v23
	v_sub_f32_e32 v23, v154, v30
	v_add_f32_e32 v22, v169, v22
	v_exp_f32_e32 v176, v23
	v_sub_f32_e32 v23, v155, v30
	v_add_f32_e32 v22, v170, v22
	v_exp_f32_e32 v180, v23
	v_sub_f32_e32 v23, v156, v30
	v_add_f32_e32 v22, v171, v22
	v_exp_f32_e32 v178, v23
	v_sub_f32_e32 v23, v157, v30
	v_add_f32_e32 v22, v172, v22
	v_exp_f32_e32 v182, v23
	v_sub_f32_e32 v23, v158, v30
	v_add_f32_e32 v22, v176, v22
	v_exp_f32_e32 v184, v23
	v_sub_f32_e32 v23, v159, v30
	v_add_f32_e32 v22, v180, v22
	v_exp_f32_e32 v186, v23
	v_sub_f32_e32 v23, v160, v30
	v_add_f32_e32 v22, v178, v22
	v_exp_f32_e32 v188, v23
	v_sub_f32_e32 v23, v161, v30
	v_add_f32_e32 v22, v182, v22
	v_exp_f32_e32 v173, v23
	v_sub_f32_e32 v23, v162, v30
	v_add_f32_e32 v22, v184, v22
	v_exp_f32_e32 v177, v23
	v_sub_f32_e32 v23, v163, v30
	v_add_f32_e32 v22, v186, v22
	v_exp_f32_e32 v181, v23
	v_sub_f32_e32 v23, v164, v30
	v_add_f32_e32 v22, v188, v22
	v_exp_f32_e32 v179, v23
	v_sub_f32_e32 v23, v166, v30
	v_add_f32_e32 v22, v173, v22
	v_exp_f32_e32 v183, v23
	v_sub_f32_e32 v23, v167, v30
	v_add_f32_e32 v22, v177, v22
	v_exp_f32_e32 v185, v23
	v_sub_f32_e32 v23, v174, v30
	v_add_f32_e32 v22, v181, v22
	v_exp_f32_e32 v187, v23
	v_sub_f32_e32 v23, v175, v30
	v_add_f32_e32 v22, v179, v22
	v_exp_f32_e32 v189, v23
	v_add_f32_e32 v22, v183, v22
	v_add_f32_e32 v22, v185, v22
	v_add_f32_e32 v22, v187, v22
	v_add_f32_e32 v23, v189, v22
	v_sub_f32_e32 v22, v190, v30
	v_exp_f32_e32 v22, v22
	v_sub_f32_e32 v24, v191, v30
	v_exp_f32_e32 v24, v24
	v_sub_f32_e32 v25, v192, v30
	v_exp_f32_e32 v26, v25
	v_sub_f32_e32 v25, v193, v30
	v_exp_f32_e32 v28, v25
	v_sub_f32_e32 v25, v194, v30
	v_add_f32_e32 v23, v22, v23
	v_exp_f32_e32 v200, v25
	v_sub_f32_e32 v25, v195, v30
	v_add_f32_e32 v23, v24, v23
	v_exp_f32_e32 v201, v25
	v_sub_f32_e32 v25, v196, v30
	v_add_f32_e32 v23, v26, v23
	v_exp_f32_e32 v198, v25
	v_sub_f32_e32 v25, v197, v30
	v_add_f32_e32 v23, v28, v23
	v_exp_f32_e32 v199, v25
	v_add_f32_e32 v23, v200, v23
	v_add_f32_e32 v23, v201, v23
	v_add_f32_e32 v23, v198, v23
	v_add_f32_e32 v31, v199, v23
	v_sub_f32_e32 v23, v247, v30
	v_exp_f32_e32 v23, v23
	v_sub_f32_e32 v25, v248, v30
	v_exp_f32_e32 v25, v25
	v_sub_f32_e32 v27, v249, v30
	v_exp_f32_e32 v27, v27
	v_sub_f32_e32 v29, v250, v30
	v_exp_f32_e32 v29, v29
	v_sub_f32_e32 v32, v165, v30
	v_add_f32_e32 v31, v23, v31
	v_exp_f32_e32 v154, v32
	v_sub_f32_e32 v32, v127, v30
	v_add_f32_e32 v31, v25, v31
	v_exp_f32_e32 v155, v32
	v_sub_f32_e32 v32, v251, v30
	v_add_f32_e32 v31, v27, v31
	v_exp_f32_e32 v156, v32
	v_sub_f32_e32 v32, v252, v30
	v_add_f32_e32 v31, v29, v31
	v_exp_f32_e32 v157, v32
	v_sub_f32_e32 v32, v215, v30
	v_add_f32_e32 v31, v154, v31
	v_exp_f32_e32 v164, v32
	v_add_f32_e32 v31, v155, v31
	v_sub_f32_e32 v32, v34, v30
	v_add_f32_e32 v31, v156, v31
	v_exp_f32_e32 v162, v32
	v_sub_f32_e32 v32, v137, v30
	v_add_f32_e32 v31, v157, v31
	v_exp_f32_e32 v160, v32
	v_sub_f32_e32 v1, v1, v30
	v_exp_f32_e32 v158, v1
	v_add_f32_e32 v1, v164, v31
	v_sub_f32_e32 v31, v234, v30
	v_exp_f32_e32 v165, v31
	v_sub_f32_e32 v31, v75, v30
	v_add_f32_e32 v1, v162, v1
	v_exp_f32_e32 v163, v31
	v_sub_f32_e32 v31, v82, v30
	v_add_f32_e32 v1, v160, v1
	v_exp_f32_e32 v161, v31
	v_sub_f32_e32 v31, v77, v30
	v_add_f32_e32 v1, v158, v1
	v_exp_f32_e32 v159, v31
	v_sub_f32_e32 v14, v14, v30
	v_add_f32_e32 v1, v165, v1
	v_exp_f32_e32 v166, v14
	v_sub_f32_e32 v14, v15, v30
	v_add_f32_e32 v1, v163, v1
	v_exp_f32_e32 v167, v14
	v_sub_f32_e32 v14, v16, v30
	v_add_f32_e32 v1, v161, v1
	v_exp_f32_e32 v174, v14
	v_sub_f32_e32 v14, v17, v30
	v_add_f32_e32 v1, v159, v1
	v_exp_f32_e32 v175, v14
	v_add_f32_e32 v1, v166, v1
	v_add_f32_e32 v1, v167, v1
	v_add_f32_e32 v1, v174, v1
	v_add_f32_e32 v1, v175, v1
	ds_bpermute_b32 v14, v41, v1
	v_lshl_add_u64 v[190:191], v[78:79], 0, s[8:9]
	v_lshlrev_b32_e32 v196, 1, v136
	v_lshlrev_b32_e32 v192, 1, v80
	s_waitcnt lgkmcnt(0)
; #define MFMA32(a, b, c) __builtin_amdgcn_mfma_f32_32x32x16_bf16((a), (b), (c), 0, 0, 0)
; DI void cmp_task(const bf16_t* Z, const bf16_t* KCC, const bf16_t* VCT, bf16_t* OCMP, unsigned* selm, int b, int hk, int tg, int lane) {
;     ...
;     const float lt = sum + __shfl_xor(sum, 32); const float inv = lt > 0.f ? 1.0f / lt : 0.f;
; #pragma unroll
;     for (int sub = 0; sub < 4; ++sub)
; #pragma unroll
;         for (int r = 0; r < 16; ++r) p[sub][r] *= inv;
;     f32x16 o0 = f16zero(), o1 = f16zero();
; #pragma unroll
;     for (int sub = 0; sub < 4; ++sub) if (sub < nsub) {
; #pragma unroll
;         for (int s2 = 0; s2 < 2; ++s2) {
;             const bf16x8 pf = pack8(p[sub], s2);
; #pragma unroll
;             for (int dt = 0; dt < 2; ++dt) {
;                 const bf16_t* wp = vt + (size_t)(32 * dt + r32) * 128 + 32 * sub + 16 * s2 + 4 * h;
;                 const u32x2 lo = *(const u32x2*)wp, hi = *(const u32x2*)(wp + 8);
;                 const u32x4 w4 = {lo.x, lo.y, hi.x, hi.y}; const bf16x8 vf = __builtin_bit_cast(bf16x8, w4);
;                 if (dt == 0) o0 = MFMA32(vf, pf, o0); else o1 = MFMA32(vf, pf, o1);
	v_add_f32_e32 v1, v1, v14
	v_div_scale_f32 v14, s[78:79], v1, v1, 1.0
	v_rcp_f32_e32 v15, v14
	s_nop 0
	v_fma_f32 v16, -v14, v15, 1.0
	v_fmac_f32_e32 v15, v16, v15
	v_div_scale_f32 v16, vcc, 1.0, v1, 1.0
	v_mul_f32_e32 v17, v16, v15
	v_fma_f32 v30, -v14, v17, v16
	v_fmac_f32_e32 v17, v30, v15
	v_fma_f32 v14, -v14, v17, v16
	v_div_fmas_f32 v14, v14, v15, v17
	v_div_fixup_f32 v14, v14, v1, 1.0
	v_cmp_lt_f32_e32 vcc, 0, v1
	s_nop 1
	v_cndmask_b32_e32 v194, 0, v14, vcc
	v_pk_mul_f32 v[130:131], v[12:13], v[194:195] op_sel_hi:[1,0]
	v_pk_mul_f32 v[134:135], v[10:11], v[194:195] op_sel_hi:[1,0]
	v_pk_mul_f32 v[124:125], v[18:19], v[194:195] op_sel_hi:[1,0]
	v_pk_mul_f32 v[126:127], v[20:21], v[194:195] op_sel_hi:[1,0]
	v_pk_mul_f32 v[140:141], v[22:23], v[194:195] op_sel_hi:[1,0]
	v_pk_mul_f32 v[142:143], v[8:9], v[194:195] op_sel_hi:[1,0]
	v_pk_mul_f32 v[144:145], v[24:25], v[194:195] op_sel_hi:[1,0]
	v_pk_mul_f32 v[148:149], v[6:7], v[194:195] op_sel_hi:[1,0]
	v_pk_mul_f32 v[146:147], v[26:27], v[194:195] op_sel_hi:[1,0]
	v_pk_mul_f32 v[150:151], v[4:5], v[194:195] op_sel_hi:[1,0]
	v_pk_mul_f32 v[128:129], v[28:29], v[194:195] op_sel_hi:[1,0]
	v_pk_mul_f32 v[152:153], v[2:3], v[194:195] op_sel_hi:[1,0]
	v_mbcnt_lo_u32_b32 v215, -1, 0
	v_mbcnt_hi_u32_b32 v215, -1, v215
	v_lshrrev_b32_e32 v77, 5, v215
	v_and_b32_e32 v215, 31, v215
	v_lshlrev_b32_e32 v215, 4, v215
	v_lshl_or_b32 v215, v77, 3, v215
	v_add_u32_e32 v215, s99, v215
	s_waitcnt vmcnt(0)
	s_andn2_b64 vcc, exec, s[10:11]
	s_cbranch_vccnz .LBB0_491
	v_mov_b32_e32 v197, v43
	v_lshl_add_u64 v[96:97], v[190:191], 0, v[196:197]
	ds_read_b64 v[2:3], v215 offset:0
	ds_read_b64 v[4:5], v215 offset:512
	v_mov_b32_e32 v193, v43
	v_lshl_add_u64 v[234:235], v[190:191], 0, v[192:193]
	ds_read_b64 v[22:23], v215 offset:8192
	ds_read_b64 v[24:25], v215 offset:8704
	ds_read_b64 v[94:95], v215 offset:1024
	s_nop 0
	ds_read_b64 v[96:97], v215 offset:1536
	v_cvt_pk_bf16_f32 v18, v130, v134
	v_cvt_pk_bf16_f32 v19, v131, v135
	v_cvt_pk_bf16_f32 v20, v142, v148
	v_cvt_pk_bf16_f32 v21, v150, v152
	v_cvt_pk_bf16_f32 v248, v124, v125
	v_cvt_pk_bf16_f32 v249, v126, v127
	v_cvt_pk_bf16_f32 v250, v143, v149
	v_cvt_pk_bf16_f32 v251, v151, v153
	s_waitcnt lgkmcnt(4)
	v_mfma_f32_32x32x16_bf16 v[2:17], v[2:5], v[18:21], 0
	s_waitcnt lgkmcnt(0)
	v_mfma_f32_32x32x16_bf16 v[2:17], v[94:97], v[248:251], v[2:17]
	ds_read_b64 v[94:95], v215 offset:9216
	ds_read_b64 v[96:97], v215 offset:9728
	v_mfma_f32_32x32x16_bf16 v[18:33], v[22:25], v[18:21], 0
	s_waitcnt lgkmcnt(0)
	v_mfma_f32_32x32x16_bf16 v[18:33], v[94:97], v[248:251], v[18:33]
	s_branch .LBB0_492

; #define MFMA32(a, b, c) __builtin_amdgcn_mfma_f32_32x32x16_bf16((a), (b), (c), 0, 0, 0)
; DI void cmp_task(const bf16_t* Z, const bf16_t* KCC, const bf16_t* VCT, bf16_t* OCMP, unsigned* selm, int b, int hk, int tg, int lane) {
;     ...
; #pragma unroll
;     for (int sub = 0; sub < 4; ++sub) if (sub < nsub) {
; #pragma unroll
;         for (int s2 = 0; s2 < 2; ++s2) {
;             const bf16x8 pf = pack8(p[sub], s2);
; #pragma unroll
;             for (int dt = 0; dt < 2; ++dt) {
;                 const bf16_t* wp = vt + (size_t)(32 * dt + r32) * 128 + 32 * sub + 16 * s2 + 4 * h;
;                 const u32x2 lo = *(const u32x2*)wp, hi = *(const u32x2*)(wp + 8);
;                 const u32x4 w4 = {lo.x, lo.y, hi.x, hi.y}; const bf16x8 vf = __builtin_bit_cast(bf16x8, w4);
;                 if (dt == 0) o0 = MFMA32(vf, pf, o0); else o1 = MFMA32(vf, pf, o1);
;             }
;         }
;     }
.LBB0_492:
	v_mov_b32_e32 v195, v194
	v_pk_mul_f32 v[168:169], v[168:169], v[194:195]
	v_pk_mul_f32 v[170:171], v[170:171], v[194:195]
	v_pk_mul_f32 v[172:173], v[172:173], v[194:195]
	v_pk_mul_f32 v[176:177], v[176:177], v[194:195]
	v_pk_mul_f32 v[180:181], v[180:181], v[194:195]
	v_pk_mul_f32 v[178:179], v[178:179], v[194:195]
	v_pk_mul_f32 v[182:183], v[182:183], v[194:195]
	v_pk_mul_f32 v[184:185], v[184:185], v[194:195]
	v_pk_mul_f32 v[186:187], v[186:187], v[194:195]
	s_andn2_b64 vcc, exec, s[48:49]
	v_pk_mul_f32 v[188:189], v[188:189], v[194:195]
	s_cbranch_vccnz .LBB0_494
	v_mov_b32_e32 v197, v43
	v_lshl_add_u64 v[234:235], v[190:191], 0, v[196:197]
	ds_read_b64 v[248:249], v215 offset:2048
	ds_read_b64 v[250:251], v215 offset:2560
	v_mov_b32_e32 v193, v43
	v_cvt_pk_bf16_f32 v94, v168, v169
	v_cvt_pk_bf16_f32 v95, v170, v171
	v_cvt_pk_bf16_f32 v96, v172, v176
	v_cvt_pk_bf16_f32 v97, v180, v178
	v_lshl_add_u64 v[34:35], v[190:191], 0, v[192:193]
	s_waitcnt lgkmcnt(0)
	v_mfma_f32_32x32x16_bf16 v[2:17], v[248:251], v[94:97], v[2:17]
	ds_read_b64 v[248:249], v215 offset:10240
	ds_read_b64 v[250:251], v215 offset:10752
	s_waitcnt lgkmcnt(0)
	v_mfma_f32_32x32x16_bf16 v[18:33], v[248:251], v[94:97], v[18:33]
	ds_read_b64 v[248:249], v215 offset:3072
	ds_read_b64 v[250:251], v215 offset:3584
	v_cvt_pk_bf16_f32 v94, v182, v184
	v_cvt_pk_bf16_f32 v95, v186, v188
	v_cvt_pk_bf16_f32 v96, v173, v177
	v_cvt_pk_bf16_f32 v97, v181, v179
	s_waitcnt lgkmcnt(0)
	s_nop 0
	v_mfma_f32_32x32x16_bf16 v[2:17], v[248:251], v[94:97], v[2:17]
	ds_read_b64 v[248:249], v215 offset:11264
	ds_read_b64 v[250:251], v215 offset:11776
	s_waitcnt lgkmcnt(0)
	v_mfma_f32_32x32x16_bf16 v[18:33], v[248:251], v[94:97], v[18:33]
.LBB0_494:
	v_pk_mul_f32 v[200:201], v[200:201], v[194:195]
	s_andn2_b64 vcc, exec, s[50:51]
	v_pk_mul_f32 v[198:199], v[198:199], v[194:195]
	s_cbranch_vccnz .LBB0_496
	v_mov_b32_e32 v197, v43
	v_lshl_add_u64 v[34:35], v[190:191], 0, v[196:197]
	ds_read_b64 v[248:249], v215 offset:4096
	ds_read_b64 v[250:251], v215 offset:4608
	v_mov_b32_e32 v193, v43
	v_cvt_pk_bf16_f32 v94, v183, v185
	v_cvt_pk_bf16_f32 v95, v187, v189
	v_cvt_pk_bf16_f32 v96, v140, v144
	v_cvt_pk_bf16_f32 v97, v146, v128
	v_lshl_add_u64 v[234:235], v[190:191], 0, v[192:193]
	s_waitcnt lgkmcnt(0)
	v_mfma_f32_32x32x16_bf16 v[2:17], v[248:251], v[94:97], v[2:17]
	ds_read_b64 v[248:249], v215 offset:12288
	ds_read_b64 v[250:251], v215 offset:12800
	s_waitcnt lgkmcnt(0)
	v_mfma_f32_32x32x16_bf16 v[18:33], v[248:251], v[94:97], v[18:33]
	ds_read_b64 v[248:249], v215 offset:5120
	ds_read_b64 v[250:251], v215 offset:5632
	v_cvt_pk_bf16_f32 v94, v200, v201
	v_cvt_pk_bf16_f32 v95, v198, v199
	v_cvt_pk_bf16_f32 v96, v141, v145
	v_cvt_pk_bf16_f32 v97, v147, v129
	s_waitcnt lgkmcnt(0)
	s_nop 0
	v_mfma_f32_32x32x16_bf16 v[2:17], v[248:251], v[94:97], v[2:17]
	ds_read_b64 v[248:249], v215 offset:13312
	ds_read_b64 v[250:251], v215 offset:13824
	s_waitcnt lgkmcnt(0)
	v_mfma_f32_32x32x16_bf16 v[18:33], v[248:251], v[94:97], v[18:33]
.LBB0_496:
	v_pk_mul_f32 v[154:155], v[154:155], v[194:195]
	v_pk_mul_f32 v[156:157], v[156:157], v[194:195]
	v_pk_mul_f32 v[164:165], v[164:165], v[194:195]
	v_pk_mul_f32 v[162:163], v[162:163], v[194:195]
	v_pk_mul_f32 v[160:161], v[160:161], v[194:195]
	s_andn2_b64 vcc, exec, s[52:53]
	v_pk_mul_f32 v[158:159], v[158:159], v[194:195]
	s_cbranch_vccnz .LBB0_498
	v_mov_b32_e32 v197, v43
	v_pk_mul_f32 v[34:35], v[166:167], v[194:195]
	v_pk_mul_f32 v[166:167], v[174:175], v[194:195]
	v_lshl_add_u64 v[174:175], v[190:191], 0, v[196:197]
	ds_read_b64 v[194:195], v215 offset:6144
	ds_read_b64 v[196:197], v215 offset:6656
	v_cvt_pk_bf16_f32 v94, v154, v155
	v_cvt_pk_bf16_f32 v95, v156, v157
	v_cvt_pk_bf16_f32 v96, v164, v162
	v_cvt_pk_bf16_f32 v97, v160, v158
	v_mov_b32_e32 v193, v43
	s_waitcnt lgkmcnt(0)
	v_mfma_f32_32x32x16_bf16 v[2:17], v[194:197], v[94:97], v[2:17]
	v_lshl_add_u64 v[194:195], v[190:191], 0, v[192:193]
	ds_read_b64 v[190:191], v215 offset:14336
	ds_read_b64 v[192:193], v215 offset:14848
	s_waitcnt lgkmcnt(0)
	v_mfma_f32_32x32x16_bf16 v[18:33], v[190:193], v[94:97], v[18:33]
	ds_read_b64 v[190:191], v215 offset:7168
	ds_read_b64 v[192:193], v215 offset:7680
	v_cvt_pk_bf16_f32 v94, v165, v163
	v_cvt_pk_bf16_f32 v95, v161, v159
	v_cvt_pk_bf16_f32 v96, v34, v35
	v_cvt_pk_bf16_f32 v97, v166, v167
	s_waitcnt lgkmcnt(0)
	s_nop 0
	v_mfma_f32_32x32x16_bf16 v[2:17], v[190:193], v[94:97], v[2:17]
	ds_read_b64 v[190:191], v215 offset:15360
	ds_read_b64 v[192:193], v215 offset:15872
	s_waitcnt lgkmcnt(0)
	v_mfma_f32_32x32x16_bf16 v[18:33], v[190:193], v[94:97], v[18:33]
